# v90 re-measure (same file)
# baseline (speedup 1.0000x reference)
.LBB0_6:
	s_mov_b32 s98, 0
	v_writelane_b32 v255, s98, 20
	s_add_u32 s54, s88, 0xe400000
	s_addc_u32 s55, s89, 0
	s_add_u32 s4, s88, 0x100000
	s_addc_u32 s5, s89, 0
	v_writelane_b32 v251, s4, 3
	s_cmp_gt_i32 s90, -1
	s_load_dwordx16 s[12:27], s[0:1], 0x40
	v_writelane_b32 v251, s5, 4
	s_cselect_b64 s[4:5], -1, 0
	s_add_u32 s96, s0, 0xd0
	v_writelane_b32 v251, s4, 5
	s_addc_u32 s97, s1, 0
	v_lshrrev_b32_e32 v1, 20, v0
	v_writelane_b32 v251, s5, 6
	s_add_u32 s4, s88, 0x1200
	s_addc_u32 s5, s89, 0
	v_writelane_b32 v251, s4, 7
	v_lshrrev_b32_e32 v0, 10, v0
	v_or_b32_e32 v0, v0, v1
	v_writelane_b32 v251, s5, 8
	s_add_u32 s4, s88, 0x1400
	s_addc_u32 s5, s89, 0
	v_writelane_b32 v251, s4, 9
	s_load_dwordx16 s[72:87], s[0:1], 0x0
	s_load_dwordx16 s[56:71], s[0:1], 0x80
	v_writelane_b32 v251, s5, 10
	s_add_u32 s4, s88, 0x1500
	s_addc_u32 s5, s89, 0
	v_writelane_b32 v251, s4, 11
	s_brev_b32 s0, 1
	v_mov_b32_e32 v1, 0
	v_writelane_b32 v251, s5, 12
	s_add_u32 s4, s88, 0x1600
	s_addc_u32 s5, s89, 0
	v_writelane_b32 v251, s4, 13
	v_mbcnt_lo_u32_b32 v2, -1, 0
	v_mov_b32_e32 v157, 1
	v_writelane_b32 v251, s5, 14
	s_add_u32 s4, s88, 0x1700
	s_addc_u32 s5, s89, 0
	v_writelane_b32 v251, s4, 15
	v_mov_b32_e32 v218, 0x358637bd
	v_mov_b32_e32 v219, 0x1f8
	v_writelane_b32 v251, s5, 16
	s_add_u32 s4, s88, 0x1800
	s_addc_u32 s5, s89, 0
	v_writelane_b32 v251, s4, 17
	v_mov_b32_e32 v154, 0xbf1f24be
	v_mov_b32_e32 v156, 0x3e642e9d
	v_writelane_b32 v251, s5, 18
	s_add_u32 s4, s88, 0x1900
	s_addc_u32 s5, s89, 0
	v_writelane_b32 v251, s4, 19
	v_mbcnt_hi_u32_b32 v220, -1, v2
	v_mov_b32_e32 v250, 0x100
	v_writelane_b32 v251, s5, 20
	s_add_u32 s4, s88, 0x1a00
	s_addc_u32 s5, s89, 0
	v_writelane_b32 v251, s4, 21
	v_mov_b32_e32 v221, 0x200
	v_mov_b32_e32 v228, 0x80
	v_writelane_b32 v251, s5, 22
	s_add_u32 s4, s88, 0x1b00
	s_addc_u32 s5, s89, 0
	v_writelane_b32 v251, s4, 23
	v_mov_b32_e32 v229, 0x42800000
	v_not_b32_e32 v230, 63
	v_writelane_b32 v251, s5, 24
	s_add_u32 s4, s88, 0x1c00
	s_addc_u32 s5, s89, 0
	v_writelane_b32 v251, s4, 25
	v_mov_b64_e32 v[158:159], 0x550
	v_mov_b64_e32 v[160:161], 0x54f
	v_writelane_b32 v251, s5, 26
	s_add_u32 s4, s88, 0x1d00
	s_addc_u32 s5, s89, 0
	v_writelane_b32 v251, s4, 27
	v_mov_b64_e32 v[162:163], 0x200
	v_mov_b64_e32 v[164:165], 0x1ff
	v_writelane_b32 v251, s5, 28
	s_add_u32 s4, s88, 0x1e00
	s_addc_u32 s5, s89, 0
	v_writelane_b32 v251, s4, 29
	v_mov_b32_e32 v231, 0x7f800000
	v_mov_b32_e32 v232, 0x7fc00000
	v_writelane_b32 v251, s5, 30
	s_add_u32 s4, s88, 0x1f00
	s_addc_u32 s5, s89, 0
	v_writelane_b32 v251, s4, 31
	s_mov_b32 s40, 0x8000
	s_movk_i32 s33, 0x6000
	v_writelane_b32 v251, s5, 32
	s_add_u32 s4, s88, 0x2000
	s_addc_u32 s5, s89, 0
	v_writelane_b32 v251, s4, 33
	s_nop 1
	v_writelane_b32 v251, s5, 34
	s_add_u32 s4, s88, 0x2100
	s_addc_u32 s5, s89, 0
	v_writelane_b32 v251, s4, 35
	s_nop 1
	v_writelane_b32 v251, s5, 36
	s_add_u32 s4, s88, 0x2200
	s_addc_u32 s5, s89, 0
	v_writelane_b32 v251, s4, 37
	s_nop 1
	v_writelane_b32 v251, s5, 38
	s_add_u32 s4, s88, 0x2300
	s_addc_u32 s5, s89, 0
	v_writelane_b32 v251, s4, 39
	s_cmp_eq_u32 s8, 15
	s_nop 0
	v_writelane_b32 v251, s5, 40
	s_cselect_b64 s[4:5], -1, 0
	v_writelane_b32 v251, s4, 41
	s_cmp_eq_u32 s8, 14
	s_nop 0
	v_writelane_b32 v251, s5, 42
	s_cselect_b64 s[4:5], -1, 0
	v_writelane_b32 v251, s4, 43
	s_cmp_eq_u32 s8, 13
	s_nop 0
	v_writelane_b32 v251, s5, 44
	s_cselect_b64 s[4:5], -1, 0
	v_writelane_b32 v251, s4, 45
	s_cmp_eq_u32 s8, 12
	s_nop 0
	v_writelane_b32 v251, s5, 46
	s_cselect_b64 s[4:5], -1, 0
	v_writelane_b32 v251, s4, 47
	s_cmp_eq_u32 s8, 11
	s_nop 0
	v_writelane_b32 v251, s5, 48
	s_cselect_b64 s[4:5], -1, 0
	v_writelane_b32 v251, s4, 49
	s_cmp_eq_u32 s8, 10
	s_nop 0
	v_writelane_b32 v251, s5, 50
	s_cselect_b64 s[4:5], -1, 0
	v_writelane_b32 v251, s4, 51
	s_cmp_eq_u32 s8, 9
	s_nop 0
	v_writelane_b32 v251, s5, 52
	s_cselect_b64 s[4:5], -1, 0
	v_writelane_b32 v251, s4, 53
	s_cmp_eq_u32 s8, 8
	s_nop 0
	v_writelane_b32 v251, s5, 54
	s_cselect_b64 s[4:5], -1, 0
	v_writelane_b32 v251, s4, 55
	s_cmp_eq_u32 s8, 7
	s_nop 0
	v_writelane_b32 v251, s5, 56
	s_cselect_b64 s[4:5], -1, 0
	v_writelane_b32 v251, s4, 57
	s_cmp_eq_u32 s8, 6
	s_nop 0
	v_writelane_b32 v251, s5, 58
	s_cselect_b64 s[4:5], -1, 0
	v_writelane_b32 v251, s4, 59
	s_cmp_eq_u32 s8, 5
	s_nop 0
	v_writelane_b32 v251, s5, 60
	s_cselect_b64 s[4:5], -1, 0
	v_writelane_b32 v251, s4, 61
	s_cmp_eq_u32 s8, 4
	s_nop 0
	v_writelane_b32 v251, s5, 62
	s_cselect_b64 s[4:5], -1, 0
	v_writelane_b32 v251, s4, 63
	s_cmp_eq_u32 s8, 3
	v_readlane_b32 s9, v251, 0
	v_writelane_b32 v252, s5, 0
	s_cselect_b64 s[4:5], -1, 0
	v_writelane_b32 v252, s4, 1
	s_cmp_eq_u32 s8, 2
	s_nop 0
	v_writelane_b32 v252, s5, 2
	s_cselect_b64 s[4:5], -1, 0
	v_writelane_b32 v252, s4, 3
	s_cmp_eq_u32 s8, 1
	s_nop 0
	v_writelane_b32 v252, s5, 4
	s_cselect_b64 s[4:5], -1, 0
	v_writelane_b32 v252, s4, 5
	s_cmp_eq_u32 s8, 0
	s_nop 0
	v_writelane_b32 v252, s5, 6
	s_cselect_b64 s[4:5], -1, 0
	v_writelane_b32 v252, s4, 7
	s_nop 1
	v_writelane_b32 v252, s5, 8
	s_lshl_b32 s4, s8, 8
	s_add_u32 s2, s2, s4
	s_addc_u32 s3, s3, 0
	s_add_u32 s4, s2, 0x1400
	s_addc_u32 s5, s3, 0
	v_writelane_b32 v252, s4, 9
	s_add_u32 s2, s2, 0x2400
	s_addc_u32 s3, s3, 0
	v_writelane_b32 v252, s5, 10
	v_writelane_b32 v252, s2, 11
	s_nop 1
	v_writelane_b32 v252, s3, 12
	s_add_u32 s2, s88, 0x4400
	s_addc_u32 s3, s89, 0
	v_writelane_b32 v252, s2, 13
	s_nop 1
	v_writelane_b32 v252, s3, 14
	s_add_u32 s2, s88, 0x4500
	s_addc_u32 s3, s89, 0
	v_writelane_b32 v252, s2, 15
	s_nop 1
	v_writelane_b32 v252, s3, 16
	s_lshl_b32 s2, s9, 3
	s_cmp_eq_u32 s9, 0
	v_writelane_b32 v252, s2, 17
	s_cselect_b64 s[2:3], -1, 0
	v_writelane_b32 v252, s2, 18
	s_nop 1
	v_writelane_b32 v252, s3, 19
	s_add_u32 s2, s88, 0x8000
	s_addc_u32 s3, s89, 0
	v_writelane_b32 v252, s2, 20
	s_add_u32 s42, s88, 0x240000
	s_addc_u32 s43, s89, 0
	v_writelane_b32 v252, s3, 21
	s_lshl_b32 s2, s9, 9
	s_cmpk_lt_i32 s9, 0x200
	v_writelane_b32 v252, s2, 22
	s_cselect_b64 s[2:3], -1, 0
	v_writelane_b32 v252, s2, 23
	s_nop 1
	v_writelane_b32 v252, s3, 24
	s_add_u32 s2, s88, 0x6000000
	s_addc_u32 s3, s89, 0
	v_writelane_b32 v252, s2, 25
	s_nop 1
	v_writelane_b32 v252, s3, 26
	s_add_u32 s2, s88, 0x200000
	s_addc_u32 s3, s89, 0
	v_writelane_b32 v252, s2, 27
	s_cmpk_lt_i32 s9, 0x100
	s_nop 0
	v_writelane_b32 v252, s3, 28
	s_cselect_b64 s[2:3], -1, 0
	v_writelane_b32 v252, s2, 29
	s_nop 1
	v_writelane_b32 v252, s3, 30
	s_add_u32 s2, s88, 0x400000
	v_writelane_b32 v252, s2, 31
	s_addc_u32 s2, s89, 0
	s_cmpk_lt_i32 s9, 0x80
	v_writelane_b32 v252, s2, 32
	s_cselect_b64 s[2:3], -1, 0
	v_writelane_b32 v252, s2, 33
	s_nop 1
	v_writelane_b32 v252, s3, 34
	s_waitcnt lgkmcnt(0)
	v_writelane_b32 v252, s12, 35
	s_add_u32 s2, s12, 0x400
	s_addc_u32 s3, s13, 0
	v_writelane_b32 v252, s13, 36
	v_writelane_b32 v252, s14, 37
	v_writelane_b32 v252, s15, 38
	v_writelane_b32 v252, s16, 39
	v_writelane_b32 v252, s17, 40
	v_writelane_b32 v252, s18, 41
	v_writelane_b32 v252, s19, 42
	v_writelane_b32 v252, s20, 43
	v_writelane_b32 v252, s21, 44
	v_writelane_b32 v252, s22, 45
	v_writelane_b32 v252, s23, 46
	v_writelane_b32 v252, s24, 47
	v_writelane_b32 v252, s25, 48
	v_writelane_b32 v252, s26, 49
	v_writelane_b32 v252, s27, 50
	v_writelane_b32 v252, s2, 51
	s_cmpk_lt_i32 s9, 0x300
	s_mov_b32 s21, 0
	v_writelane_b32 v252, s3, 52
	s_cselect_b64 s[2:3], -1, 0
	s_add_u32 s10, s88, 0xa000000
	v_writelane_b32 v252, s2, 53
	s_addc_u32 s11, s89, 0
	s_mov_b32 s13, s21
	v_writelane_b32 v252, s3, 54
	s_add_u32 s2, s88, 0x4000000
	v_writelane_b32 v252, s2, 55
	s_addc_u32 s2, s89, 0
	v_writelane_b32 v252, s2, 56
	s_add_u32 s2, s88, 0x2000000
	v_writelane_b32 v252, s2, 57
	s_addc_u32 s2, s89, 0
	v_writelane_b32 v252, s2, 58
	s_add_u32 s2, s88, 0x1800000
	v_writelane_b32 v252, s2, 59
	s_addc_u32 s2, s89, 0
	v_writelane_b32 v252, s2, 60
	s_add_u32 s2, s88, 0x10e00000
	s_addc_u32 s3, s89, 0
	v_writelane_b32 v252, s2, 61
	s_mov_b64 s[26:27], 0x80
	s_nop 0
	v_writelane_b32 v252, s3, 62
	s_add_u32 s2, s88, 0x11f00000
	s_addc_u32 s3, s89, 0
	v_writelane_b32 v252, s2, 63
	s_nop 1
	v_writelane_b32 v253, s3, 0
	s_add_u32 s2, s88, 0x17400000
	v_writelane_b32 v253, s2, 1
	s_addc_u32 s2, s89, 0
	v_writelane_b32 v253, s2, 2
	s_add_u32 s2, s88, 0x15200000
	s_addc_u32 s3, s89, 0
	v_writelane_b32 v253, s2, 3
	s_nop 1
	v_writelane_b32 v253, s3, 4
	s_add_u32 s2, s88, 0x16300000
	s_addc_u32 s3, s89, 0
	v_writelane_b32 v253, s2, 5
	s_nop 1
	v_writelane_b32 v253, s3, 6
	s_add_u32 s2, s88, 0x18500000
	v_writelane_b32 v253, s2, 7
	s_addc_u32 s2, s89, 0
	v_writelane_b32 v253, s2, 8
	s_add_u32 s2, s88, 0x14100000
	s_addc_u32 s3, s89, 0
	v_writelane_b32 v253, s2, 9
	s_nop 1
	v_writelane_b32 v253, s3, 10
	s_add_u32 s2, s88, 0x13000000
	s_addc_u32 s3, s89, 0
	v_writelane_b32 v253, s2, 11
	s_cmpk_lt_i32 s9, 0x550
	s_nop 0
	v_writelane_b32 v253, s3, 12
	s_cselect_b64 s[2:3], -1, 0
	v_writelane_b32 v253, s2, 13
	s_nop 1
	v_writelane_b32 v253, s3, 14
	s_ashr_i32 s2, s9, 31
	v_writelane_b32 v253, s2, 15
	s_lshr_b32 s2, s2, 29
	s_add_i32 s2, s9, s2
	s_ashr_i32 s7, s2, 3
	s_and_b32 s2, s2, -8
	s_sub_i32 s5, s9, s2
	s_add_u32 s2, s88, 0x10c00000
	v_writelane_b32 v253, s2, 16
	s_addc_u32 s2, s89, 0
	s_add_u32 s52, s88, 0xec00000
	s_addc_u32 s53, s89, 0
	v_writelane_b32 v253, s2, 17
	s_add_u32 s2, s88, 0x6100000
	s_addc_u32 s3, s89, 0
	v_writelane_b32 v253, s2, 18
	s_cmpk_lt_i32 s9, 0x80
	s_nop 0
	v_writelane_b32 v253, s3, 19
	s_cselect_b64 s[2:3], -1, 0
	v_writelane_b32 v253, s2, 20
	s_lshl_b32 s4, s5, 6
	s_bfe_u32 s12, s9, 0x20002
	v_writelane_b32 v253, s3, 21
	s_ashr_i32 s2, s9, 4
	s_addk_i32 s2, 0x80
	s_ashr_i32 s3, s2, 31
	v_writelane_b32 v253, s2, 22
	s_nop 1
	v_writelane_b32 v253, s3, 23
	s_and_b32 s2, s9, 3
	s_cmp_lt_i32 s5, 0
	v_writelane_b32 v253, s2, 24
	s_cselect_b64 s[2:3], -1, 0
	v_writelane_b32 v253, s2, 25
	s_nop 1
	v_writelane_b32 v253, s3, 26
	s_and_b64 s[2:3], s[2:3], exec
	s_movk_i32 s3, 0xab
	s_cselect_b32 s3, s3, 0xaa
	s_mul_i32 s2, s5, 0x41
	s_mul_i32 s3, s5, s3
	s_cselect_b32 s2, s2, s4
	s_add_i32 s3, s3, s7
	s_mul_hi_i32 s4, s3, 0x66666667
	v_writelane_b32 v253, s5, 27
	s_lshr_b32 s5, s4, 31
	s_ashr_i32 s4, s4, 4
	s_add_i32 s4, s4, s5
	s_mul_i32 s5, s4, 40
	s_sub_i32 s3, s3, s5
	s_bfe_i32 s5, s3, 0x80000
	s_bfe_u32 s5, s5, 0x2000d
	s_add_i32 s5, s3, s5
	s_and_b32 s6, s5, 0xfc
	s_add_i32 s2, s2, s7
	s_sub_i32 s3, s3, s6
	s_ashr_i32 s6, s2, 31
	s_lshr_b32 s6, s6, 28
	s_add_i32 s6, s2, s6
	v_writelane_b32 v253, s7, 28
	s_and_b32 s7, s6, 0xfff0
	s_sub_i32 s2, s2, s7
	s_bfe_i32 s7, s2, 0x80000
	s_bfe_u32 s7, s7, 0x2000d
	s_add_i32 s7, s2, s7
	s_and_b32 s8, s7, 0xfc
	s_lshl_b32 s4, s4, 2
	s_sext_i32_i8 s3, s3
	s_sub_i32 s2, s2, s8
	s_add_i32 s14, s4, s3
	s_ashr_i32 s3, s6, 4
	s_lshl_b32 s3, s3, 2
	s_sext_i32_i8 s2, s2
	s_add_i32 s2, s3, s2
	s_bfe_i32 s4, s7, 0x80000
	s_ashr_i32 s3, s2, 31
	s_sext_i32_i16 s4, s4
	v_writelane_b32 v253, s2, 29
	s_bfe_i32 s5, s5, 0x80000
	s_sext_i32_i16 s5, s5
	v_writelane_b32 v253, s3, 30
	s_ashr_i32 s2, s4, 2
	v_writelane_b32 v253, s2, 31
	s_lshr_b32 s2, s4, 2
	s_bfe_i64 s[2:3], s[2:3], 0x100000
	v_writelane_b32 v253, s2, 32
	s_ashr_i32 s15, s14, 31
	s_nop 0
	v_writelane_b32 v253, s3, 33
	s_ashr_i32 s2, s5, 2
	v_writelane_b32 v253, s2, 34
	s_lshr_b32 s2, s5, 2
	s_bfe_i64 s[2:3], s[2:3], 0x100000
	s_lshl_b64 s[2:3], s[2:3], 19
	v_writelane_b32 v253, s2, 35
	s_nop 1
	v_writelane_b32 v253, s3, 36
	s_mov_b32 s2, s14
	v_writelane_b32 v253, s2, 37
	s_nop 1
	v_writelane_b32 v253, s3, 38
	s_lshl_b64 s[2:3], s[14:15], 19
	s_add_u32 s4, s10, s2
	v_writelane_b32 v253, s10, 39
	s_addc_u32 s5, s11, s3
	s_movk_i32 s2, 0x3ff
	v_writelane_b32 v253, s11, 40
	v_writelane_b32 v253, s12, 41
	v_and_or_b32 v0, v0, s2, v155
	s_add_u32 s2, s4, 0x40000
	v_writelane_b32 v253, s13, 42
	v_writelane_b32 v253, s4, 43
	s_addc_u32 s3, s5, 0
	s_mov_b32 s13, 0x800000
	v_writelane_b32 v253, s5, 44
	v_writelane_b32 v253, s2, 45
	s_movk_i32 s14, 0x7fff
	s_mov_b32 s15, 0x8800
	v_writelane_b32 v253, s3, 46
	s_lshl_b32 s2, s9, 10
	v_writelane_b32 v253, s2, 47
	s_lshl_b32 s2, s9, 4
	v_writelane_b32 v253, s2, 48
	s_add_u32 s2, s88, 0x16310000
	s_addc_u32 s3, s89, 0
	v_writelane_b32 v253, s2, 49
	s_mov_b32 s12, s90
	s_nop 0
	v_writelane_b32 v253, s3, 50
	s_add_u32 s2, s88, 0x18502100
	s_addc_u32 s3, s89, 0
	v_writelane_b32 v253, s2, 51
	s_nop 1
	v_writelane_b32 v253, s3, 52
	s_add_u32 s2, s88, 0x18500100
	s_addc_u32 s3, s89, 0
	v_writelane_b32 v253, s2, 53
	s_nop 1
	v_writelane_b32 v253, s3, 54
	s_add_u32 s2, s88, 0x20080
	v_writelane_b32 v253, s2, 55
	s_addc_u32 s2, s89, 0
	v_writelane_b32 v253, s2, 56
	s_add_u32 s2, s88, 0x100
	v_writelane_b32 v253, s2, 57
	s_addc_u32 s2, s89, 0
	v_writelane_b32 v253, s2, 58
	s_add_i32 s2, 0, 0x20010
	v_writelane_b32 v253, s2, 59
	s_add_i32 s2, 0, 0x20014
	v_writelane_b32 v253, s2, 60
	s_add_i32 s2, 0, 0x20000
	v_writelane_b32 v253, s2, 61
	s_add_i32 s2, 0, 0x21c00
	v_writelane_b32 v253, s2, 62
	s_add_i32 s2, 0, 0x21400
	v_writelane_b32 v253, s2, 63
	s_add_i32 s2, 0, 0x217a0
	v_writelane_b32 v254, s2, 0
	s_add_i32 s2, 0, 0x11100
	v_writelane_b32 v254, s2, 1
	v_cmp_eq_u32_e64 s[2:3], 0, v0
	s_nop 1
	v_writelane_b32 v254, s2, 2
	s_nop 1
	v_writelane_b32 v254, s3, 3
	v_writelane_b32 v254, s56, 4
	s_nop 1
	v_writelane_b32 v254, s57, 5
	v_writelane_b32 v254, s58, 6
	v_writelane_b32 v254, s59, 7
	v_writelane_b32 v254, s60, 8
	v_writelane_b32 v254, s61, 9
	v_writelane_b32 v254, s62, 10
	v_writelane_b32 v254, s63, 11
	v_writelane_b32 v254, s64, 12
	v_writelane_b32 v254, s65, 13
	v_writelane_b32 v254, s66, 14
	v_writelane_b32 v254, s67, 15
	v_writelane_b32 v254, s68, 16
	v_writelane_b32 v254, s69, 17
	v_writelane_b32 v254, s70, 18
	v_writelane_b32 v254, s71, 19
	v_writelane_b32 v254, s0, 20
	v_readlane_b32 s56, v252, 35
	v_readlane_b32 s57, v252, 36
	v_writelane_b32 v254, s1, 21
	v_writelane_b32 v254, s2, 22
	v_writelane_b32 v254, s3, 23
	v_writelane_b32 v254, s4, 24
	v_writelane_b32 v254, s5, 25
	v_writelane_b32 v254, s6, 26
	v_writelane_b32 v254, s7, 27
	v_writelane_b32 v254, s8, 28
	v_writelane_b32 v254, s9, 29
	v_writelane_b32 v254, s10, 30
	v_writelane_b32 v254, s11, 31
	v_writelane_b32 v254, s12, 32
	v_writelane_b32 v254, s13, 33
	v_writelane_b32 v254, s14, 34
	v_writelane_b32 v254, s15, 35
	v_writelane_b32 v254, s42, 36
	v_readlane_b32 s58, v252, 37
	v_readlane_b32 s59, v252, 38
	v_writelane_b32 v254, s43, 37
	v_writelane_b32 v254, s72, 38
	v_readlane_b32 s66, v252, 45
	v_readlane_b32 s67, v252, 46
	v_writelane_b32 v254, s73, 39
	v_writelane_b32 v254, s74, 40
	v_writelane_b32 v254, s75, 41
	v_writelane_b32 v254, s76, 42
	v_writelane_b32 v254, s77, 43
	v_writelane_b32 v254, s78, 44
	v_writelane_b32 v254, s79, 45
	v_writelane_b32 v254, s80, 46
	v_writelane_b32 v254, s81, 47
	v_writelane_b32 v254, s82, 48
	v_writelane_b32 v254, s83, 49
	v_writelane_b32 v254, s84, 50
	v_writelane_b32 v254, s85, 51
	v_writelane_b32 v254, s86, 52
	v_readlane_b32 s70, v252, 49
	v_readlane_b32 s71, v252, 50
	v_writelane_b32 v254, s87, 53
	v_readlane_b32 s60, v252, 39
	v_readlane_b32 s61, v252, 40
	v_readlane_b32 s62, v252, 41
	v_readlane_b32 s63, v252, 42
	v_readlane_b32 s64, v252, 43
	v_readlane_b32 s65, v252, 44
	v_readlane_b32 s68, v252, 47
	v_readlane_b32 s69, v252, 48
	s_branch .LBB0_9

.Lmy_tf_done:
	v_readlane_b32 s98, v255, 20
	s_mov_b32 s99, 0x20408
	s_cmp_lg_u32 s98, 0
	s_cbranch_scc1 .Lprobe_adv
	s_bitcmp1_b32 s99, s12
	s_cbranch_scc0 .Lprobe_adv
	s_mov_b32 s98, 1
	v_writelane_b32 v255, s98, 20
	s_branch .LBB0_9
	s_nop 0
	s_nop 0
	s_nop 0
	s_nop 0
	s_nop 0
	s_nop 0
	s_nop 0
	s_nop 0
	s_nop 0
	s_nop 0
	s_nop 0
	s_nop 0
	s_nop 0
	s_nop 0
	s_nop 0
	s_nop 0
	s_nop 0
	s_nop 0
	s_nop 0
	s_nop 0
	s_nop 0
	s_nop 0
	s_nop 0
	s_nop 0
	s_nop 0
	s_nop 0
	s_nop 0
	s_nop 0
	s_nop 0
	s_nop 0
	s_nop 0
	s_nop 0
	s_nop 0
	s_nop 0
	s_nop 0
	s_nop 0
	s_nop 0
	s_nop 0
	s_nop 0
	s_nop 0
	s_nop 0
.Lprobe_adv:
	s_mov_b32 s98, 0
	v_writelane_b32 v255, s98, 20
	s_add_i32 s12, s12, 1
	s_cmp_ge_i32 s12, s91
	s_cbranch_scc0 .LBB0_9
	s_getpc_b64 s[98:99]

.LBB0_86:
	s_andn2_b64 vcc, exec, s[2:3]
	v_writelane_b32 v254, s12, 54
	s_cbranch_vccnz .LBB0_570
	s_add_i32 s0, s12, -1
	s_mul_hi_i32 s1, s0, 0x92492493
	s_add_i32 s1, s1, s0
	s_lshr_b32 s2, s1, 31
	s_ashr_i32 s1, s1, 2
	s_add_i32 s2, s1, s2
	s_mul_i32 s1, s2, 7
	s_sub_i32 s47, s0, s1
	s_sub_i32 s0, s12, 22
	s_cmp_lt_u32 s0, 7
	s_cselect_b64 s[38:39], -1, 0
	s_cmp_gt_u32 s0, 6
	s_cselect_b64 s[0:1], -1, 0
	v_writelane_b32 v254, s0, 55
	s_mov_b64 s[50:51], 0
	s_nop 0
	v_writelane_b32 v254, s1, 56
	s_add_i32 s0, s12, 5
	v_readlane_b32 s56, v254, 4
	s_cmp_lt_u32 s0, 13
	v_readlane_b32 s70, v254, 18
	v_readlane_b32 s71, v254, 19
	s_cselect_b32 s48, s73, s71
	s_cselect_b32 s49, s72, s70
	s_ashr_i32 s3, s2, 31
	v_readlane_b32 s57, v254, 5
	v_readlane_b32 s58, v254, 6
	v_readlane_b32 s59, v254, 7
	v_readlane_b32 s60, v254, 8
	v_readlane_b32 s61, v254, 9
	v_readlane_b32 s62, v254, 10
	v_readlane_b32 s63, v254, 11
	v_readlane_b32 s64, v254, 12
	v_readlane_b32 s65, v254, 13
	v_readlane_b32 s66, v254, 14
	v_readlane_b32 s67, v254, 15
	v_readlane_b32 s68, v254, 16
	v_readlane_b32 s69, v254, 17
	s_mul_hi_i32 s0, s2, 0x36000
	v_writelane_b32 v254, s2, 57
	s_mul_i32 s1, s2, 0x36000
	s_mov_b64 s[58:59], 0
	v_writelane_b32 v254, s3, 58
	v_readlane_b32 s2, v251, 3
	v_readlane_b32 s3, v251, 4
	s_add_u32 s44, s2, s1
	s_addc_u32 s45, s3, s0
	v_writelane_b32 v254, s44, 59
	s_mov_b64 s[0:1], -1
	s_cmp_lt_i32 s47, 1
	v_writelane_b32 v254, s45, 60
	v_writelane_b32 v254, s47, 61
	s_cbranch_scc1 .LBB0_414
	s_cmp_gt_i32 s47, 1
	s_cbranch_scc0 .LBB0_263
	s_cmp_eq_u32 s47, 2
	s_mov_b64 s[58:59], -1
	s_cbranch_scc0 .LBB0_262
	s_and_b64 s[0:1], s[38:39], exec
	s_movk_i32 s0, 0x600
	s_cselect_b32 s37, s0, 0x610
	s_movk_i32 s0, 0x618
	s_cselect_b32 s41, 0x600, s0
	s_movk_i32 s0, 0x638
	s_cselect_b32 s92, 0x600, s0
	s_movk_i32 s0, 0x658
	s_cselect_b32 s93, 0x600, s0
	s_movk_i32 s0, 0x918
	v_readlane_b32 s18, v254, 57
	s_cselect_b32 s94, 0x600, s0
	s_lshl_b32 s0, s18, 6
	s_ashr_i32 s1, s0, 31
	s_lshl_b64 s[0:1], s[0:1], 2
	s_add_u32 s22, s88, s0
	s_addc_u32 s23, s89, s1
	v_readlane_b32 s98, v255, 20
	s_lshl_b32 s98, s98, 6
	s_add_u32 s22, s22, s98
	s_addc_u32 s23, s23, 0
	s_lshl_b32 s16, s18, 9
	v_readlane_b32 s19, v254, 58
	s_add_i32 s2, s18, 1
	v_writelane_b32 v254, s16, 62
	s_ashr_i32 s3, s2, 31
	s_waitcnt lgkmcnt(0)
	s_lshl_b32 s8, s18, 1
	s_lshl_b32 s10, s18, 8
	v_readlane_b32 s72, v254, 4
	s_lshl_b64 s[4:5], s[2:3], 24
	s_lshl_b64 s[6:7], s[2:3], 23
	s_lshl_b32 s95, s18, 2
	s_ashr_i32 s9, s8, 31
	s_ashr_i32 s11, s10, 31
	v_readlane_b32 s82, v254, 14
	v_readlane_b32 s83, v254, 15
	s_add_u32 s16, s82, s4
	s_addc_u32 s17, s83, s5
	v_readlane_b32 s73, v254, 5
	v_readlane_b32 s74, v254, 6
	v_readlane_b32 s75, v254, 7
	v_readlane_b32 s76, v254, 8
	v_readlane_b32 s77, v254, 9
	v_readlane_b32 s78, v254, 10
	v_readlane_b32 s79, v254, 11
	v_readlane_b32 s80, v254, 12
	v_readlane_b32 s81, v254, 13
	v_readlane_b32 s84, v254, 16
	v_readlane_b32 s85, v254, 17
	v_readlane_b32 s86, v254, 18
	v_readlane_b32 s87, v254, 19
	v_writelane_b32 v254, s16, 63
	v_readlane_b32 s56, v252, 35
	v_readlane_b32 s58, v252, 37
	v_writelane_b32 v255, s17, 0
	v_readlane_b32 s16, v252, 55
	s_add_u32 s24, s16, s6
	v_readlane_b32 s16, v252, 56
	s_addc_u32 s25, s16, s7
	v_writelane_b32 v255, s24, 1
	s_add_u32 s4, s80, s4
	s_addc_u32 s5, s81, s5
	v_writelane_b32 v255, s25, 2
	v_writelane_b32 v255, s4, 3
	v_readlane_b32 s59, v252, 38
	s_mul_hi_i32 s12, s2, 0x900000
	v_writelane_b32 v255, s5, 4
	v_readlane_b32 s4, v252, 57
	s_add_u32 s6, s4, s6
	v_readlane_b32 s4, v252, 58
	s_addc_u32 s7, s4, s7
	s_lshl_b64 s[4:5], s[2:3], 22
	v_writelane_b32 v255, s6, 5
	s_add_u32 s4, s58, s4
	s_addc_u32 s5, s59, s5
	v_writelane_b32 v255, s7, 6
	v_writelane_b32 v255, s4, 7
	s_mul_i32 s13, s2, 0x900000
	s_mul_hi_i32 s14, s2, 0x500000
	s_mul_i32 s15, s2, 0x500000
	v_writelane_b32 v255, s5, 8
	s_lshl_b64 s[2:3], s[2:3], 21
	v_readlane_b32 s4, v252, 59
	s_add_u32 s4, s4, s2
	v_readlane_b32 s2, v252, 60
	s_addc_u32 s5, s2, s3
	v_readlane_b32 s57, v252, 36
	s_add_u32 s2, s56, s13
	s_addc_u32 s3, s57, s12
	v_writelane_b32 v255, s4, 9
	s_add_u32 s2, s2, 0x400
	s_addc_u32 s3, s3, 0
	v_writelane_b32 v255, s5, 10
	v_writelane_b32 v255, s2, 11
	v_readlane_b32 s4, v252, 20
	v_readlane_b32 s5, v252, 21
	v_writelane_b32 v255, s3, 12
	s_add_u32 s2, s88, s15
	s_addc_u32 s3, s89, s14
	s_add_u32 s2, s2, 0x500000
	s_addc_u32 s3, s3, 0
	v_writelane_b32 v255, s2, 13
	v_readlane_b32 s70, v252, 49
	v_readlane_b32 s71, v252, 50
	v_writelane_b32 v255, s3, 14
	s_lshl_b64 s[2:3], s[8:9], 2
	s_add_u32 s2, s4, s2
	s_addc_u32 s3, s5, s3
	s_add_u32 s0, s78, s0
	s_addc_u32 s1, s79, s1
	v_readlane_b32 s62, v252, 41
	v_readlane_b32 s66, v252, 45
	v_readlane_b32 s67, v252, 46
	s_mov_b64 s[70:71], s[0:1]
	s_lshl_b64 s[0:1], s[10:11], 2
	v_readlane_b32 s63, v252, 42
	s_mov_b64 s[66:67], s[2:3]
	s_add_u32 s2, s62, s0
	v_readlane_b32 s64, v252, 43
	s_addc_u32 s3, s63, s1
	v_readlane_b32 s65, v252, 44
	v_writelane_b32 v255, s2, 15
	s_add_u32 s0, s64, s0
	s_addc_u32 s1, s65, s1
	v_writelane_b32 v255, s3, 16
	v_writelane_b32 v255, s0, 17
	v_readlane_b32 s60, v252, 39
	v_readlane_b32 s61, v252, 40
	v_writelane_b32 v255, s1, 18
	s_mul_i32 s0, s18, 0x744
	v_readlane_b32 s68, v252, 47
	v_readlane_b32 s69, v252, 48
	s_mov_b32 s13, 0x800000
	s_mov_b64 s[64:65], s[22:23]
	v_writelane_b32 v255, s0, 19
	s_mov_b64 s[10:11], 0x8000
	v_readfirstlane_b32 s98, v155
	s_lshr_b32 s98, s98, 6
	s_cmp_lg_u32 s98, 0
	s_cbranch_scc1 .Ldq_noprime
	s_mov_b64 s[0:1], exec
	s_mov_b32 s2, 0
	s_mov_b32 s3, 1
	s_mov_b64 exec, s[2:3]
	global_atomic_add v255, v1, v157, s[64:65] sc0
	s_mov_b64 exec, s[0:1]

.LBB0_94:
	s_barrier
	s_mov_b64 s[0:1], exec
	v_readfirstlane_b32 s98, v155
	s_lshr_b32 s98, s98, 6
	s_cmp_lg_u32 s98, 0
	s_cbranch_scc1 .LBB0_98
	s_waitcnt vmcnt(0)
	v_readlane_b32 s98, v255, 32
	s_cmp_ge_u32 s98, s93
	s_cbranch_scc1 .Ldq_done
	s_cmp_lt_u32 s98, 0x200
	s_cbranch_scc0 .Ldq_o0
	s_add_i32 s98, s98, 0x100
	s_branch .Ldq_done
	s_nop 0
	s_nop 0
	s_nop 0
	s_nop 0
	s_nop 0
	s_nop 0
	s_nop 0
	s_nop 0
	s_nop 0
	s_nop 0
	s_nop 0
	s_nop 0
	s_nop 0
	s_nop 0
	s_nop 0
	s_nop 0
	s_nop 0
	s_nop 0
	s_nop 0
	s_nop 0
	s_nop 0
	s_nop 0
	s_nop 0
	s_nop 0
	s_nop 0
	s_nop 0
	s_nop 0
	s_nop 0
	s_nop 0
	s_nop 0
.Ldq_o0:
	s_sub_i32 s98, s98, 0x200
	s_cmp_lt_u32 s98, 0x100
	s_cbranch_scc0 .Ldq_o1
	s_branch .Ldq_done
.Ldq_o1:
	s_sub_i32 s98, s98, 0x100
	s_sub_i32 s99, s93, s37
	s_cmp_lt_u32 s98, s99
	s_cbranch_scc0 .Ldq_o2
	s_add_i32 s98, s98, s37
	s_branch .Ldq_done
